# attention preamble: 8 serialized gain-max load round trips issued as one burst
# speedup vs baseline: 1.0010x; 1.0010x over previous
; __device__ __forceinline__ void phase3(const Params& p, LAS unsigned char* lds, int tid, int lane, int wave) {
;     float mq = 0.f, mk = 0.f;
;     for (int i = 0; i < 64; ++i) { mq = fmaxf(mq, fabsf(p.qg[i])); mk = fmaxf(mk, fabsf(p.kg[i])); }
;     const float mshift = 8.f * LOG2E * 1.03f * mq * mk;
;     const int G = gridDim.x, bx = blockIdx.x; const int vcu = (G % 8 == 0) ? (bx % 8) * (G / 8) + bx / 8 : bx;
;     for (int pr = vcu; pr < 256; pr += G) { const int bh = pr >> 2, s = pr & 3;
.LBB0_346:
	global_load_dwordx4 v[4:7], v2, s[8:9]
	global_load_dwordx4 v[8:11], v2, s[8:9] offset:16
	global_load_dwordx4 v[12:15], v2, s[8:9] offset:32
	global_load_dwordx4 v[16:19], v2, s[8:9] offset:48
	global_load_dwordx4 v[20:23], v2, s[8:9] offset:64
	global_load_dwordx4 v[24:27], v2, s[8:9] offset:80
	global_load_dwordx4 v[28:31], v2, s[8:9] offset:96
	global_load_dwordx4 v[32:35], v2, s[8:9] offset:112
	global_load_dwordx4 v[36:39], v2, s[8:9] offset:128
	global_load_dwordx4 v[40:43], v2, s[8:9] offset:144
	global_load_dwordx4 v[44:47], v2, s[8:9] offset:160
	global_load_dwordx4 v[48:51], v2, s[8:9] offset:176
	global_load_dwordx4 v[52:55], v2, s[8:9] offset:192
	global_load_dwordx4 v[56:59], v2, s[8:9] offset:208
	global_load_dwordx4 v[60:63], v2, s[8:9] offset:224
	global_load_dwordx4 v[64:67], v2, s[8:9] offset:240
	global_load_dwordx4 v[68:71], v2, s[10:11]
	global_load_dwordx4 v[72:75], v2, s[10:11] offset:16
	global_load_dwordx4 v[76:79], v2, s[10:11] offset:32
	global_load_dwordx4 v[80:83], v2, s[10:11] offset:48
	global_load_dwordx4 v[84:87], v2, s[10:11] offset:64
	global_load_dwordx4 v[88:91], v2, s[10:11] offset:80
	global_load_dwordx4 v[92:95], v2, s[10:11] offset:96
	global_load_dwordx4 v[96:99], v2, s[10:11] offset:112
	global_load_dwordx4 v[100:103], v2, s[10:11] offset:128
	global_load_dwordx4 v[104:107], v2, s[10:11] offset:144
	global_load_dwordx4 v[108:111], v2, s[10:11] offset:160
	global_load_dwordx4 v[112:115], v2, s[10:11] offset:176
	global_load_dwordx4 v[116:119], v2, s[10:11] offset:192
	global_load_dwordx4 v[120:123], v2, s[10:11] offset:208
	global_load_dwordx4 v[124:127], v2, s[10:11] offset:224
	global_load_dwordx4 v[128:131], v2, s[10:11] offset:240
	s_waitcnt vmcnt(16)
	v_max3_f32 v1, v1, |v4|, |v5|
	v_max3_f32 v1, v1, |v6|, |v7|
	v_max3_f32 v1, v1, |v8|, |v9|
	v_max3_f32 v1, v1, |v10|, |v11|
	v_max3_f32 v1, v1, |v12|, |v13|
	v_max3_f32 v1, v1, |v14|, |v15|
	v_max3_f32 v1, v1, |v16|, |v17|
	v_max3_f32 v1, v1, |v18|, |v19|
	v_max3_f32 v1, v1, |v20|, |v21|
	v_max3_f32 v1, v1, |v22|, |v23|
	v_max3_f32 v1, v1, |v24|, |v25|
	v_max3_f32 v1, v1, |v26|, |v27|
	v_max3_f32 v1, v1, |v28|, |v29|
	v_max3_f32 v1, v1, |v30|, |v31|
	v_max3_f32 v1, v1, |v32|, |v33|
	v_max3_f32 v1, v1, |v34|, |v35|
	v_max3_f32 v1, v1, |v36|, |v37|
	v_max3_f32 v1, v1, |v38|, |v39|
	v_max3_f32 v1, v1, |v40|, |v41|
	v_max3_f32 v1, v1, |v42|, |v43|
	v_max3_f32 v1, v1, |v44|, |v45|
	v_max3_f32 v1, v1, |v46|, |v47|
	v_max3_f32 v1, v1, |v48|, |v49|
	v_max3_f32 v1, v1, |v50|, |v51|
	v_max3_f32 v1, v1, |v52|, |v53|
	v_max3_f32 v1, v1, |v54|, |v55|
	v_max3_f32 v1, v1, |v56|, |v57|
	v_max3_f32 v1, v1, |v58|, |v59|
	v_max3_f32 v1, v1, |v60|, |v61|
	v_max3_f32 v1, v1, |v62|, |v63|
	v_max3_f32 v1, v1, |v64|, |v65|
	v_max3_f32 v1, v1, |v66|, |v67|
	s_waitcnt vmcnt(0)
	v_max3_f32 v0, v0, |v68|, |v69|
	v_max3_f32 v0, v0, |v70|, |v71|
	v_max3_f32 v0, v0, |v72|, |v73|
	v_max3_f32 v0, v0, |v74|, |v75|
	v_max3_f32 v0, v0, |v76|, |v77|
	v_max3_f32 v0, v0, |v78|, |v79|
	v_max3_f32 v0, v0, |v80|, |v81|
	v_max3_f32 v0, v0, |v82|, |v83|
	v_max3_f32 v0, v0, |v84|, |v85|
	v_max3_f32 v0, v0, |v86|, |v87|
	v_max3_f32 v0, v0, |v88|, |v89|
	v_max3_f32 v0, v0, |v90|, |v91|
	v_max3_f32 v0, v0, |v92|, |v93|
	v_max3_f32 v0, v0, |v94|, |v95|
	v_max3_f32 v0, v0, |v96|, |v97|
	v_max3_f32 v0, v0, |v98|, |v99|
	v_max3_f32 v0, v0, |v100|, |v101|
	v_max3_f32 v0, v0, |v102|, |v103|
	v_max3_f32 v0, v0, |v104|, |v105|
	v_max3_f32 v0, v0, |v106|, |v107|
	v_max3_f32 v0, v0, |v108|, |v109|
	v_max3_f32 v0, v0, |v110|, |v111|
	v_max3_f32 v0, v0, |v112|, |v113|
	v_max3_f32 v0, v0, |v114|, |v115|
	v_max3_f32 v0, v0, |v116|, |v117|
	v_max3_f32 v0, v0, |v118|, |v119|
	v_max3_f32 v0, v0, |v120|, |v121|
	v_max3_f32 v0, v0, |v122|, |v123|
	v_max3_f32 v0, v0, |v124|, |v125|
	v_max3_f32 v0, v0, |v126|, |v127|
	v_max3_f32 v0, v0, |v128|, |v129|
	v_max3_f32 v0, v0, |v130|, |v131|
	s_movk_i32 s16, 0x100
	s_and_b32 s0, s26, 7
	s_cmp_eq_u32 s0, 0
	s_mov_b32 s3, s2
	s_cbranch_scc1 .LBB0_349
	s_cmpk_gt_i32 s3, 0xff
	s_cbranch_scc0 .LBB0_350
	s_branch .LBB0_382
